# no loop-top vmcnt(0) in two GEMM K-loops; WlT fill with all 64 loads in flight; gdn_prep wave-0 wait counted; phase G weight pointers loaded once instead of per item
# speedup vs baseline: 1.0060x; 1.0060x over previous
; __device__ __forceinline__ void phase_g(KA a, int layer, const float* x1, unsigned char* lds, const int tid_, const int bid_) {
;     ...
;     for (int it = gw; it < 16384; it += NGW) {
;         const bool up = it < 8192; const int r = up ? it : it - 8192;
;         const float* W = up ? a->in[18] + (size_t)layer * D_ * DFF : a->in[19] + (size_t)layer * DFF * D_;
;         bf16_t* WT = (bf16_t*)(ws + (up ? WS_WUP : WS_WDN)); const int K = up ? D_ : DFF, N = up ? DFF : D_;
;         const int nblk = N / 32, kb = r / nblk, nb = r % nblk;
;         transpose_tile(W + (size_t)(64 * kb) * N + 32 * nb, (size_t)N, WT + (size_t)(32 * nb) * K + 64 * kb, (size_t)K, scr, lane);
.LBB0_45:
	s_load_dword s7, s[94:95], 0x0
	v_ashrrev_i32_e32 v0, 6, v198
	v_lshl_add_u32 v42, s28, 3, v0
	v_and_b32_e32 v48, 63, v198
	s_waitcnt lgkmcnt(0)
	s_lshl_b32 s8, s7, 3
	s_movk_i32 s7, 0x4000
	v_cmp_gt_i32_e32 vcc, s7, v42
	s_ashr_i32 s7, s6, 31
	s_and_saveexec_b64 s[10:11], vcc
	s_cbranch_execz .LBB0_48
	s_load_dwordx2 s[18:19], s[2:3], 0x90
	s_load_dwordx2 s[20:21], s[2:3], 0x98
	s_waitcnt lgkmcnt(0)
	v_mov_b32_e32 v60, s18
	v_mov_b32_e32 v61, s19
	v_mov_b32_e32 v62, s20
	v_mov_b32_e32 v63, s21
	v_lshl_add_u32 v3, v0, 14, 0
	v_lshlrev_b32_e32 v0, 2, v48
	v_lshlrev_b32_e32 v2, 3, v48
	v_lshrrev_b32_e32 v30, 3, v48
	v_and_b32_e32 v0, 28, v0
	v_and_b32_e32 v2, 56, v2
	v_lshl_add_u32 v4, v0, 2, v3
	v_mul_u32_u24_e32 v5, 0x84, v30
	v_mul_u32_u24_e32 v6, 0x84, v2
	v_lshlrev_b32_e32 v7, 2, v30
	s_lshl_b64 s[12:13], s[6:7], 26
	v_mov_b32_e32 v31, v1
	v_or_b32_e32 v32, 8, v30
	v_mov_b32_e32 v33, v1
	v_or_b32_e32 v34, 16, v30
	v_mov_b32_e32 v35, v1
	v_or_b32_e32 v36, 24, v30
	v_mov_b32_e32 v37, v1
	v_or_b32_e32 v43, 32, v30
	v_or_b32_e32 v49, 40, v30
	v_or_b32_e32 v50, 48, v30
	v_or_b32_e32 v51, 56, v30
	v_add3_u32 v52, v3, v6, v7
	s_mov_b64 s[14:15], 0
	v_lshlrev_b32_e32 v38, 2, v0
	v_add_u32_e32 v53, v4, v5
	v_lshlrev_b32_e32 v40, 1, v2
	v_mov_b32_e32 v54, v42
; #define LDS_WAIT() asm volatile("s_waitcnt lgkmcnt(0)" ::: "memory")
; __device__ __forceinline__ unsigned cvt_pk_bf16(float lo, float hi) { f32x2 v = {lo, hi}; bf16x2_t r = __builtin_convertvector(v, bf16x2_t); return __builtin_bit_cast(unsigned, r); }
; __device__ __forceinline__ void transpose_tile(const float* src, size_t ldw, bf16_t* dst, size_t ldk, float* scr, int lane) {
;     f32x4 v[8];
; #pragma unroll
;     for (int i = 0; i < 8; ++i) v[i] = __builtin_nontemporal_load((const f32x4*)(src + (size_t)((lane >> 3) + 8 * i) * ldw + 4 * (lane & 7)));
; #pragma unroll
;     for (int i = 0; i < 8; ++i) { float* p = scr + ((lane >> 3) + 8 * i) * 33 + 4 * (lane & 7); p[0] = v[i].x; p[1] = v[i].y; p[2] = v[i].z; p[3] = v[i].w; }
;     LDS_WAIT();
;     const int c = lane & 7;
; #pragma unroll
;     for (int j = 0; j < 4; ++j) { const int n = (lane >> 3) + 8 * j; const float* s = scr + (8 * c) * 33 + n;
;         u32x4 o; o.x = cvt_pk_bf16(s[0 * 33], s[1 * 33]); o.y = cvt_pk_bf16(s[2 * 33], s[3 * 33]); o.z = cvt_pk_bf16(s[4 * 33], s[5 * 33]); o.w = cvt_pk_bf16(s[6 * 33], s[7 * 33]);
;         *(u32x4*)(dst + (size_t)n * ldk + 8 * c) = o; }
;     LDS_WAIT();
; }
; __device__ __forceinline__ void phase_g(KA a, int layer, const float* x1, unsigned char* lds, const int tid_, const int bid_) {
;     ...
;     for (int it = gw; it < 16384; it += NGW) {
;         const bool up = it < 8192; const int r = up ? it : it - 8192;
;         const float* W = up ? a->in[18] + (size_t)layer * D_ * DFF : a->in[19] + (size_t)layer * DFF * D_;
;         bf16_t* WT = (bf16_t*)(ws + (up ? WS_WUP : WS_WDN)); const int K = up ? D_ : DFF, N = up ? DFF : D_;
;         const int nblk = N / 32, kb = r / nblk, nb = r % nblk;
;         transpose_tile(W + (size_t)(64 * kb) * N + 32 * nb, (size_t)N, WT + (size_t)(32 * nb) * K + 64 * kb, (size_t)K, scr, lane);
.LBB0_47:
	s_movk_i32 s9, 0x2000
	v_cmp_gt_i32_e64 s[40:41], s9, v54
	v_add_u32_e32 v0, 0xffffe000, v54
	v_mov_b32_e32 v2, 0x1800000
	v_cndmask_b32_e64 v6, v0, v54, s[40:41]
	v_mov_b32_e32 v0, 0x100
	v_cndmask_b32_e64 v7, 64, v0, s[40:41]
	v_mov_b32_e32 v0, 0x3800000
	v_cndmask_b32_e64 v0, v0, v2, s[40:41]
	v_cndmask_b32_e64 v2, v62, v60, s[40:41]
	v_cndmask_b32_e64 v3, v63, v61, s[40:41]
	v_cvt_f32_u32_e32 v9, v7
	v_sub_u32_e32 v10, 0, v7
	v_sub_u32_e32 v8, 0, v6
	v_max_i32_e32 v8, v6, v8
	v_rcp_iflag_f32_e32 v9, v9
	v_lshl_add_u64 v[4:5], s[4:5], 0, v[0:1]
	v_ashrrev_i32_e32 v0, 31, v6
	v_cndmask_b32_e64 v41, 11, 13, s[40:41]
	v_mul_f32_e32 v9, 0x4f7ffffe, v9
	v_cvt_u32_f32_e32 v9, v9
	v_cndmask_b32_e64 v55, 13, 11, s[40:41]
	v_mov_b32_e32 v39, v1
	v_add_u32_e32 v54, s8, v54
	v_mul_lo_u32 v10, v10, v9
	v_mul_hi_u32 v10, v9, v10
	v_add_u32_e32 v9, v9, v10
	v_mul_hi_u32 v9, v8, v9
	v_mul_lo_u32 v10, v9, v7
	v_sub_u32_e32 v8, v8, v10
	v_cmp_ge_u32_e64 s[42:43], v8, v7
	v_add_u32_e32 v10, 1, v9
	v_cmp_lt_i32_e64 s[40:41], s22, v54
	v_cndmask_b32_e64 v9, v9, v10, s[42:43]
	v_sub_u32_e32 v10, v8, v7
	v_cndmask_b32_e64 v8, v8, v10, s[42:43]
	v_cmp_ge_u32_e64 s[42:43], v8, v7
	v_add_u32_e32 v8, 1, v9
	s_or_b64 s[14:15], s[40:41], s[14:15]
	v_cndmask_b32_e64 v8, v9, v8, s[42:43]
	v_xor_b32_e32 v8, v8, v0
	v_sub_u32_e32 v0, v8, v0
	v_mul_lo_u32 v7, v0, v7
	v_sub_u32_e32 v10, v6, v7
	v_lshlrev_b32_e32 v6, 6, v0
	v_ashrrev_i32_e32 v7, 31, v6
	v_lshlrev_b64 v[8:9], v41, v[6:7]
	v_lshlrev_b32_e32 v0, v41, v36
	v_lshlrev_b32_e32 v0, 2, v0
	s_nop 0
	v_lshl_add_u64 v[2:3], v[2:3], 0, s[12:13]
	v_lshl_add_u64 v[2:3], v[8:9], 2, v[2:3]
	v_lshlrev_b32_e32 v8, 5, v10
	v_ashrrev_i32_e32 v9, 31, v8
	v_lshl_add_u64 v[2:3], v[8:9], 2, v[2:3]
	v_lshlrev_b64 v[8:9], v55, v[8:9]
	v_lshl_add_u64 v[4:5], v[8:9], 1, v[4:5]
	v_lshl_add_u64 v[46:47], v[2:3], 0, v[38:39]
	v_lshlrev_b64 v[2:3], v41, v[30:31]
	v_lshl_add_u64 v[44:45], v[6:7], 1, v[4:5]
	v_lshl_add_u64 v[2:3], v[2:3], 2, v[46:47]
	v_lshl_add_u64 v[6:7], v[46:47], 0, v[0:1]
	v_lshlrev_b32_e32 v0, v41, v43
	global_load_dwordx4 v[14:17], v[2:3], off nt
	v_lshlrev_b32_e32 v0, 2, v0
	global_load_dwordx4 v[6:9], v[6:7], off nt
	v_lshlrev_b64 v[2:3], v41, v[32:33]
	v_lshl_add_u64 v[2:3], v[2:3], 2, v[46:47]
	v_lshl_add_u64 v[18:19], v[46:47], 0, v[0:1]
	global_load_dwordx4 v[10:13], v[2:3], off nt
	v_lshlrev_b32_e32 v0, v41, v49
	global_load_dwordx4 v[18:21], v[18:19], off nt
	v_lshlrev_b64 v[2:3], v41, v[34:35]
	v_lshl_add_u64 v[2:3], v[2:3], 2, v[46:47]
	global_load_dwordx4 v[2:5], v[2:3], off nt
	v_lshlrev_b32_e32 v0, 2, v0
	v_lshl_add_u64 v[22:23], v[46:47], 0, v[0:1]
	v_lshlrev_b32_e32 v0, v41, v50
	global_load_dwordx4 v[22:25], v[22:23], off nt
	v_lshlrev_b32_e32 v0, 2, v0
	v_lshl_add_u64 v[26:27], v[46:47], 0, v[0:1]
	v_lshlrev_b32_e32 v0, v41, v51
	global_load_dwordx4 v[26:29], v[26:27], off nt
	v_lshlrev_b32_e32 v0, 2, v0
	v_lshl_add_u64 v[46:47], v[46:47], 0, v[0:1]
	global_load_dwordx4 v[56:59], v[46:47], off nt
	v_add_u32_e32 v0, 0x420, v53
	v_mov_b32_e32 v41, v1
	s_waitcnt vmcnt(7)
	ds_write2_b32 v53, v14, v15 offset1:1
	ds_write2_b32 v53, v16, v17 offset0:2 offset1:3
	s_waitcnt vmcnt(5)
	ds_write2_b32 v0, v10, v11 offset1:1
	v_add_u32_e32 v0, 0x428, v53
	ds_write2_b32 v0, v12, v13 offset1:1
	v_add_u32_e32 v0, 0x840, v53
	s_waitcnt vmcnt(3)
	ds_write2_b32 v0, v2, v3 offset1:1
	v_add_u32_e32 v0, 0x848, v53
	ds_write2_b32 v0, v4, v5 offset1:1
	v_add_u32_e32 v0, 0xc60, v53
	ds_write2_b32 v0, v6, v7 offset1:1
	v_add_u32_e32 v0, 0xc68, v53
	ds_write2_b32 v0, v8, v9 offset1:1
	v_add_u32_e32 v0, 0x1080, v53
	ds_write2_b32 v0, v18, v19 offset1:1
	v_add_u32_e32 v0, 0x1088, v53
	ds_write2_b32 v0, v20, v21 offset1:1
	v_add_u32_e32 v0, 0x14a0, v53
	s_waitcnt vmcnt(2)
	ds_write2_b32 v0, v22, v23 offset1:1
	v_add_u32_e32 v0, 0x14a8, v53
	ds_write2_b32 v0, v24, v25 offset1:1
	v_add_u32_e32 v0, 0x18c0, v53
	s_waitcnt vmcnt(1)
	ds_write2_b32 v0, v26, v27 offset1:1
	v_add_u32_e32 v0, 0x18c8, v53
	ds_write2_b32 v0, v28, v29 offset1:1
	v_add_u32_e32 v0, 0x1ce0, v53
	s_waitcnt vmcnt(0)
	ds_write2_b32 v0, v56, v57 offset1:1
	v_add_u32_e32 v0, 0x1ce8, v53
	ds_write2_b32 v0, v58, v59 offset1:1
	s_waitcnt lgkmcnt(0)
	ds_read2_b32 v[8:9], v52 offset0:33 offset1:41
	ds_read2_b32 v[10:11], v52 offset1:8
	ds_read2_b32 v[12:13], v52 offset0:66 offset1:74
	ds_read2_b32 v[14:15], v52 offset0:99 offset1:107
	ds_read2_b32 v[16:17], v52 offset0:132 offset1:140
	ds_read2_b32 v[18:19], v52 offset0:165 offset1:173
	ds_read2_b32 v[20:21], v52 offset0:198 offset1:206
	ds_read2_b32 v[22:23], v52 offset0:231 offset1:239
	v_lshl_add_u64 v[6:7], v[44:45], 0, v[40:41]
	v_lshlrev_b64 v[24:25], v55, v[30:31]
	s_waitcnt lgkmcnt(6)
	v_cvt_pk_bf16_f32 v2, v10, v8
	s_waitcnt lgkmcnt(4)
	v_cvt_pk_bf16_f32 v3, v12, v14
	s_waitcnt lgkmcnt(2)
	v_cvt_pk_bf16_f32 v4, v16, v18
	s_waitcnt lgkmcnt(0)
	v_cvt_pk_bf16_f32 v5, v20, v22
	v_lshl_add_u64 v[24:25], v[24:25], 1, v[6:7]
	global_store_dwordx4 v[24:25], v[2:5], off
	v_lshlrev_b64 v[24:25], v55, v[34:35]
	v_lshl_add_u64 v[24:25], v[24:25], 1, v[6:7]
	v_cvt_pk_bf16_f32 v2, v11, v9
	v_lshlrev_b64 v[8:9], v55, v[32:33]
	v_cvt_pk_bf16_f32 v3, v13, v15
	v_cvt_pk_bf16_f32 v4, v17, v19
	v_cvt_pk_bf16_f32 v5, v21, v23
	v_lshl_add_u64 v[8:9], v[8:9], 1, v[6:7]
	global_store_dwordx4 v[8:9], v[2:5], off
	ds_read2_b32 v[8:9], v52 offset0:16 offset1:24
	ds_read2_b32 v[10:11], v52 offset0:49 offset1:57
	ds_read2_b32 v[12:13], v52 offset0:82 offset1:90
	ds_read2_b32 v[14:15], v52 offset0:115 offset1:123
	ds_read2_b32 v[16:17], v52 offset0:148 offset1:156
	ds_read2_b32 v[18:19], v52 offset0:181 offset1:189
	ds_read2_b32 v[20:21], v52 offset0:214 offset1:222
	ds_read2_b32 v[22:23], v52 offset0:247 offset1:255
	s_waitcnt lgkmcnt(6)
	v_cvt_pk_bf16_f32 v2, v8, v10
	s_waitcnt lgkmcnt(4)
	v_cvt_pk_bf16_f32 v3, v12, v14
	s_waitcnt lgkmcnt(2)
	v_cvt_pk_bf16_f32 v4, v16, v18
	s_waitcnt lgkmcnt(0)
	v_cvt_pk_bf16_f32 v5, v20, v22
	global_store_dwordx4 v[24:25], v[2:5], off
	s_nop 1
	v_cvt_pk_bf16_f32 v2, v9, v11
	v_lshlrev_b64 v[8:9], v55, v[36:37]
	v_cvt_pk_bf16_f32 v3, v13, v15
	v_cvt_pk_bf16_f32 v4, v17, v19
	v_cvt_pk_bf16_f32 v5, v21, v23
	v_lshl_add_u64 v[6:7], v[8:9], 1, v[6:7]
	global_store_dwordx4 v[6:7], v[2:5], off
	s_waitcnt lgkmcnt(0)
	s_andn2_b64 exec, exec, s[14:15]
	s_cbranch_execnz .LBB0_47

; __device__ __forceinline__ unsigned cvt_pk_bf16(float lo, float hi) { f32x2 v = {lo, hi}; bf16x2_t r = __builtin_convertvector(v, bf16x2_t); return __builtin_bit_cast(unsigned, r); }
; #define GS_STORE_A() do { _Pragma("unroll") for (int r = 0; r < 2; ++r) { const int idx = tid + 512 * r; const int o1 = (idx >> 4) * 272 + (idx & 15) * 16; \
;             *(u32x4*)(Wl + o1) = rW[r]; *(u32x4*)(QDl + o1) = rQD[r]; } \
;         if (tid < 128) *(u32x4*)(Ul + (tid >> 1) * 32 + (tid & 1) * 16) = rU; } while (0)
; #define GS_LOAD_B(n) do { const int item_ = ((b * 64 + (n)) * 8 + h); \
;         _Pragma("unroll") for (int r = 0; r < 2; ++r) { const int idx = tid + 512 * r; rK[r] = *(const u32x4*)(KDTg + (size_t)item_ * 8192 + idx * 8); } \
;         rQK = *(const u32x4*)(QKg + (size_t)item_ * 4096 + tid * 8); egl_next = EGL[item_]; } while (0)
; #define GS_STORE_B() do { _Pragma("unroll") for (int r = 0; r < 2; ++r) { const int idx = tid + 512 * r; *(u32x4*)(KDTl + (idx >> 3) * 144 + (idx & 7) * 16) = rK[r]; } \
;         *(u32x4*)(QKl + (tid >> 3) * 144 + (tid & 7) * 16) = rQK; } while (0)
; __device__ __forceinline__ void gdn_scan(KA a, int layer, unsigned char* lds, const int tid_, const int bid_) {
;     ...
;     GS_LOAD_A(0); GS_LOAD_B(0); GS_STORE_A(); GS_STORE_B(); egl_cur = egl_next;
;     if (tid < 272) *(u32x4*)(SlT + tid * 16) = (u32x4){0u, 0u, 0u, 0u};
;     GS_LOAD_A(1);
;     __syncthreads();
;     for (int n = 0; n < 64; ++n) {
;         const int tg0 = b * SEQ_ + n * 64;
;         {
;             f32x4 acc = (f32x4){0.f, 0.f, 0.f, 0.f};
; #pragma unroll
;             for (int ks = 0; ks < 4; ++ks)
;                 acc = __builtin_amdgcn_mfma_f32_16x16x32_bf16(*(const bf16x8*)(abase + (16 * i + fr) * 272 + (32 * ks + 8 * fq) * 2), *(const bf16x8*)(SlT + fr * 272 + (32 * ks + 8 * fq) * 2), acc, 0, 0, 0);
;             if (!isQ) {
;                 float vn[4];
; #pragma unroll
;                 for (int j = 0; j < 4; ++j) { const float u = __uint_as_float(((unsigned)*(const bf16_t*)(Ul + (16 * i + 4 * fq + j) * 32 + fr * 2)) << 16); vn[j] = u - acc[j]; }
;                 u32x2 w; w.x = cvt_pk_bf16(vn[0], vn[1]); w.y = cvt_pk_bf16(vn[2], vn[3]);
;                 *(u32x2*)(VNT + fr * 144 + (16 * i + 4 * fq) * 2) = w;
;             } else out = acc;
;         }
.LBB0_178:
	s_or_b64 exec, exec, s[20:21]
	s_bfe_u32 s55, s31, 0x20003
	s_bfe_u32 s56, s31, 0x10002
	s_lshr_b32 s20, s51, 3
	s_lshl_b32 s21, s55, 9
	s_lshl_b32 s53, s56, 2
	s_or_b32 s21, s21, s53
	s_and_b32 s57, s20, 3
	s_or_b32 s20, s21, s57
	s_lshl_b32 s21, s20, 2
	s_lshl_b32 s20, s20, 13
	s_or_b32 s53, s21, 0x400040
	s_bitset1_b32 s20, 17
	s_mov_b32 s21, s89
	v_lshl_add_u64 v[72:73], v[54:55], 0, s[20:21]
	s_lshl_b32 s20, s20, 1
	v_lshl_add_u64 v[76:77], v[64:65], 0, s[20:21]
	v_lshl_add_u64 v[78:79], v[66:67], 0, s[20:21]
	s_lshl_b32 s20, s55, 12
	v_add_u32_e32 v44, s20, v97
	v_ashrrev_i32_e32 v45, 31, v44
	s_lshl_b32 s21, s56, 9
	v_lshlrev_b64 v[80:81], 11, v[44:45]
	v_or_b32_e32 v0, s21, v53
	s_lshl_b32 s56, s57, 7
	v_add_u32_e32 v44, s20, v99
	v_add_u32_e32 v46, s20, v100
	v_or_b32_e32 v0, s56, v0
	v_ashrrev_i32_e32 v45, 31, v44
	v_ashrrev_i32_e32 v47, 31, v46
	v_lshlrev_b32_e32 v43, 1, v0
	s_lshl_b32 s55, s55, 22
	s_or_b32 s21, s56, s21
	v_lshlrev_b64 v[44:45], 11, v[44:45]
	v_lshlrev_b64 v[82:83], 11, v[46:47]
	v_or_b32_e32 v80, v80, v43
	s_or_b32 s21, s21, s55
	v_or_b32_e32 v82, v82, v43
	v_lshlrev_b64 v[46:47], 1, v[84:85]
	v_lshl_add_u64 v[44:45], v[68:69], 0, v[44:45]
	v_mov_b32_e32 v43, v1
	s_mov_b32 s54, 0
	v_add_lshl_u32 v0, s21, v98, 1
	v_lshl_add_u64 v[48:49], v[58:59], 0, v[46:47]
	v_lshl_add_u64 v[42:43], v[44:45], 0, v[42:43]
	v_lshl_add_u64 v[84:85], v[48:49], 0, v[0:1]
	v_lshl_add_u64 v[86:87], v[42:43], 0, v[46:47]
	s_mov_b32 s55, s54
	s_waitcnt lgkmcnt(0)
	s_barrier
.LBB0_179:
	ds_read_b128 v[42:45], v106
	ds_read_b128 v[46:49], v114 offset:64512
	s_and_b64 vcc, exec, s[46:47]
	s_waitcnt lgkmcnt(0)
	v_mfma_f32_16x16x32_bf16 v[42:45], v[42:45], v[46:49], 0
	ds_read_b128 v[46:49], v106 offset:64
	ds_read_b128 v[116:119], v114 offset:64576
	s_waitcnt lgkmcnt(0)
	v_mfma_f32_16x16x32_bf16 v[42:45], v[46:49], v[116:119], v[42:45]
	ds_read_b128 v[46:49], v106 offset:128
	ds_read_b128 v[116:119], v114 offset:64640
	s_waitcnt lgkmcnt(0)
	v_mfma_f32_16x16x32_bf16 v[42:45], v[46:49], v[116:119], v[42:45]
	ds_read_b128 v[46:49], v106 offset:192
	ds_read_b128 v[116:119], v114 offset:64704
	s_waitcnt lgkmcnt(0)
	v_mfma_f32_16x16x32_bf16 v[42:45], v[46:49], v[116:119], v[42:45]
	s_cbranch_vccnz .LBB0_181
	ds_read_u16 v0, v107 offset:62464
	ds_read_u16 v46, v107 offset:62496
	s_waitcnt lgkmcnt(0)
	v_lshlrev_b32_e32 v47, 16, v46
	v_lshlrev_b32_e32 v46, 16, v0
	s_nop 1
	v_pk_add_f32 v[42:43], v[46:47], v[42:43] neg_lo:[0,1] neg_hi:[0,1]
	ds_read_u16 v0, v107 offset:62528
	ds_read_u16 v46, v107 offset:62560
	v_cvt_pk_bf16_f32 v42, v42, v43
	s_waitcnt lgkmcnt(0)
	v_lshlrev_b32_e32 v47, 16, v46
	v_lshlrev_b32_e32 v46, 16, v0
	v_pk_add_f32 v[44:45], v[46:47], v[44:45] neg_lo:[0,1] neg_hi:[0,1]
	s_nop 0
	v_cvt_pk_bf16_f32 v43, v44, v45
	ds_write_b64 v108, v[42:43]
	s_branch .LBB0_182

; __device__ __forceinline__ unsigned cvt_pk_bf16(float lo, float hi) { f32x2 v = {lo, hi}; bf16x2_t r = __builtin_convertvector(v, bf16x2_t); return __builtin_bit_cast(unsigned, r); }
; __device__ __forceinline__ unsigned short bf16_1(float x) { return (unsigned short)(cvt_pk_bf16(x, 0.f) & 0xffffu); }
; #define GS_STORE_A() do { _Pragma("unroll") for (int r = 0; r < 2; ++r) { const int idx = tid + 512 * r; const int o1 = (idx >> 4) * 272 + (idx & 15) * 16; \
;             *(u32x4*)(Wl + o1) = rW[r]; *(u32x4*)(QDl + o1) = rQD[r]; } \
;         if (tid < 128) *(u32x4*)(Ul + (tid >> 1) * 32 + (tid & 1) * 16) = rU; } while (0)
; #define GS_LOAD_B(n) do { const int item_ = ((b * 64 + (n)) * 8 + h); \
;         _Pragma("unroll") for (int r = 0; r < 2; ++r) { const int idx = tid + 512 * r; rK[r] = *(const u32x4*)(KDTg + (size_t)item_ * 8192 + idx * 8); } \
;         rQK = *(const u32x4*)(QKg + (size_t)item_ * 4096 + tid * 8); egl_next = EGL[item_]; } while (0)
; __device__ __forceinline__ void gdn_scan(KA a, int layer, unsigned char* lds, const int tid_, const int bid_) {
;     ...
;         if (n > 0) { GS_STORE_B(); egl_cur = egl_next; }
;         if (n + 1 < 64) GS_LOAD_B(n + 1);
;         __syncthreads();
;         {
;             bf16x8 Bv[2];
; #pragma unroll
;             for (int ks = 0; ks < 2; ++ks) Bv[ks] = *(const bf16x8*)(VNT + fr * 144 + (32 * ks + 8 * fq) * 2);
;             f32x4 accS = S * egl_cur;
; #pragma unroll
;             for (int ks = 0; ks < 2; ++ks) accS = __builtin_amdgcn_mfma_f32_16x16x32_bf16(*(const bf16x8*)(KDTl + (16 * wave + fr) * 144 + (32 * ks + 8 * fq) * 2), Bv[ks], accS, 0, 0, 0);
;             S = accS;
;             { u32x2 w; w.x = cvt_pk_bf16(S[0], S[1]); w.y = cvt_pk_bf16(S[2], S[3]); *(u32x2*)(SlT + fr * 272 + (16 * wave + 4 * fq) * 2) = w; }
;             if (isQ) {
; #pragma unroll
;                 for (int ks = 0; ks < 2; ++ks) out = __builtin_amdgcn_mfma_f32_16x16x32_bf16(*(const bf16x8*)(QKl + (16 * i + fr) * 144 + (32 * ks + 8 * fq) * 2), Bv[ks], out, 0, 0, 0);
; #pragma unroll
;                 for (int j = 0; j < 4; ++j) ORAW[(size_t)(tg0 + 16 * i + 4 * fq + j) * 1024 + h * 128 + 16 * slice + fr] = bf16_1(out[j]);
;             }
;         }
;         if (n + 1 < 64) { GS_STORE_A(); if (n + 2 < 64) GS_LOAD_A(n + 2); }
.LBB0_182:
	s_add_u32 s20, s4, s53
	s_waitcnt vmcnt(7)
	ds_write_b128 v112, v[10:13] offset:34816
	s_waitcnt vmcnt(6)
	ds_write_b128 v104, v[14:17] offset:34816
	s_waitcnt vmcnt(5)
	ds_write_b128 v105, v[18:21] offset:53248
	v_lshl_add_u64 v[10:11], s[4:5], 0, v[76:77]
	v_lshl_add_u64 v[14:15], s[4:5], 0, v[78:79]
	v_lshl_add_u64 v[18:19], s[4:5], 0, v[72:73]
	s_addc_u32 s21, s5, s54
	global_load_dwordx4 v[10:13], v[10:11], off
	s_waitcnt vmcnt(5)
	v_pk_mul_f32 v[40:41], v[40:41], v[74:75] op_sel_hi:[1,0]
	global_load_dwordx4 v[14:17], v[14:15], off
	v_pk_mul_f32 v[38:39], v[38:39], v[74:75] op_sel_hi:[1,0]
	global_load_dwordx4 v[18:21], v[18:19], off
	s_and_b64 vcc, exec, s[48:49]
	global_load_dword v0, v1, s[20:21]
	s_waitcnt lgkmcnt(0)
	s_barrier
	ds_read_b128 v[46:49], v115
	ds_read_b128 v[42:45], v115 offset:64
	ds_read_b128 v[116:119], v109 offset:34816
	s_waitcnt lgkmcnt(0)
	v_mfma_f32_16x16x32_bf16 v[38:41], v[116:119], v[46:49], v[38:41]
	ds_read_b128 v[116:119], v109 offset:34880
	s_waitcnt lgkmcnt(0)
	v_mfma_f32_16x16x32_bf16 v[38:41], v[116:119], v[42:45], v[38:41]
	s_nop 7
	v_cvt_pk_bf16_f32 v116, v38, v39
	v_cvt_pk_bf16_f32 v117, v40, v41
	ds_write_b64 v110, v[116:117] offset:64512
	s_cbranch_vccnz .LBB0_184
	ds_read_b128 v[116:119], v111 offset:53248
	s_waitcnt lgkmcnt(0)
	v_mfma_f32_16x16x32_bf16 v[2:5], v[116:119], v[46:49], v[2:5]
	ds_read_b128 v[46:49], v111 offset:53312
	s_waitcnt lgkmcnt(0)
	v_mfma_f32_16x16x32_bf16 v[2:5], v[46:49], v[42:45], v[2:5]
	v_lshl_add_u64 v[42:43], s[4:5], 0, v[84:85]
	v_add_co_u32_e32 v44, vcc, 0x11820000, v42
	s_nop 5
	v_cvt_pk_bf16_f32 v46, v2, s0
	v_addc_co_u32_e32 v45, vcc, 0, v43, vcc
	global_store_short v[44:45], v46, off
	v_cvt_pk_bf16_f32 v46, v3, s0
	v_add_co_u32_e32 v42, vcc, 0x11821000, v42
	global_store_short v[44:45], v46, off offset:2048
	v_cvt_pk_bf16_f32 v44, v4, s0
	v_addc_co_u32_e32 v43, vcc, 0, v43, vcc
	global_store_short v[42:43], v44, off
	v_cvt_pk_bf16_f32 v44, v5, s0
	global_store_short v[42:43], v44, off offset:2048
.LBB0_184:
	s_waitcnt vmcnt(7)
	ds_write_b128 v101, v[26:29]
	s_waitcnt vmcnt(6)
	ds_write_b128 v101, v[22:25] offset:17408
	s_waitcnt vmcnt(5)
	ds_write_b128 v102, v[34:37]
	s_waitcnt vmcnt(4)
	ds_write_b128 v102, v[30:33] offset:17408
	s_and_saveexec_b64 s[20:21], s[40:41]
	ds_write_b128 v103, v[6:9] offset:62464
	s_or_b64 exec, exec, s[20:21]
	v_lshl_add_u64 v[22:23], s[4:5], 0, v[80:81]
	v_add_co_u32_e32 v24, vcc, 0xb800000, v22
	v_lshl_add_u64 v[30:31], s[4:5], 0, v[82:83]
	s_nop 0
	v_addc_co_u32_e32 v25, vcc, 0, v23, vcc
	v_add_co_u32_e32 v22, vcc, 0x21800000, v22
	s_nop 1
	v_addc_co_u32_e32 v23, vcc, 0, v23, vcc
	v_add_co_u32_e32 v32, vcc, 0xb800000, v30
	global_load_dwordx4 v[26:29], v[24:25], off
	s_nop 0
	global_load_dwordx4 v[22:25], v[22:23], off
	v_addc_co_u32_e32 v33, vcc, 0, v31, vcc
	v_add_co_u32_e32 v30, vcc, 0x21800000, v30
	s_nop 1
	v_addc_co_u32_e32 v31, vcc, 0, v31, vcc
	global_load_dwordx4 v[34:37], v[32:33], off
	s_nop 0
	global_load_dwordx4 v[30:33], v[30:31], off
	s_and_saveexec_b64 s[20:21], s[40:41]
	s_cbranch_execz .LBB0_188
	v_lshl_add_u64 v[6:7], s[4:5], 0, v[86:87]
	global_load_dwordx4 v[6:9], v[6:7], off
.LBB0_188:
	s_or_b64 exec, exec, s[20:21]
	s_add_i32 s55, s55, 1
	s_add_u32 s53, s53, 32
	s_addc_u32 s54, s54, 0
	s_mov_b64 s[20:21], 0x10000
	v_lshl_add_u64 v[72:73], v[72:73], 0, s[20:21]
	v_lshl_add_u64 v[76:77], v[76:77], 0, s[0:1]
	v_lshl_add_u64 v[78:79], v[78:79], 0, s[0:1]
	v_lshl_add_u64 v[80:81], v[80:81], 0, s[0:1]
	v_lshl_add_u64 v[84:85], v[84:85], 0, s[0:1]
	v_lshl_add_u64 v[86:87], v[86:87], 0, s[0:1]
	s_cmp_eq_u32 s55, 61
	v_lshl_add_u64 v[82:83], v[82:83], 0, s[0:1]
	s_waitcnt lgkmcnt(0)
	s_barrier
	s_cbranch_scc1 .LBB0_190
	s_waitcnt vmcnt(4)
	v_mov_b32_e32 v74, v0
	s_branch .LBB0_179

; __device__ __forceinline__ unsigned cvt_pk_bf16(float lo, float hi) { f32x2 v = {lo, hi}; bf16x2_t r = __builtin_convertvector(v, bf16x2_t); return __builtin_bit_cast(unsigned, r); }
; __device__ __forceinline__ unsigned short bf16_1(float x) { return (unsigned short)(cvt_pk_bf16(x, 0.f) & 0xffffu); }
; #define GS_LOAD_B(n) do { const int item_ = ((b * 64 + (n)) * 8 + h); \
;         _Pragma("unroll") for (int r = 0; r < 2; ++r) { const int idx = tid + 512 * r; rK[r] = *(const u32x4*)(KDTg + (size_t)item_ * 8192 + idx * 8); } \
;         rQK = *(const u32x4*)(QKg + (size_t)item_ * 4096 + tid * 8); egl_next = EGL[item_]; } while (0)
; #define GS_STORE_B() do { _Pragma("unroll") for (int r = 0; r < 2; ++r) { const int idx = tid + 512 * r; *(u32x4*)(KDTl + (idx >> 3) * 144 + (idx & 7) * 16) = rK[r]; } \
;         *(u32x4*)(QKl + (tid >> 3) * 144 + (tid & 7) * 16) = rQK; } while (0)
; __device__ __forceinline__ void gdn_scan(KA a, int layer, unsigned char* lds, const int tid_, const int bid_) {
;     ...
;         if (n > 0) { GS_STORE_B(); egl_cur = egl_next; }
;         if (n + 1 < 64) GS_LOAD_B(n + 1);
;         __syncthreads();
;         {
;             bf16x8 Bv[2];
; #pragma unroll
;             for (int ks = 0; ks < 2; ++ks) Bv[ks] = *(const bf16x8*)(VNT + fr * 144 + (32 * ks + 8 * fq) * 2);
;             f32x4 accS = S * egl_cur;
; #pragma unroll
;             for (int ks = 0; ks < 2; ++ks) accS = __builtin_amdgcn_mfma_f32_16x16x32_bf16(*(const bf16x8*)(KDTl + (16 * wave + fr) * 144 + (32 * ks + 8 * fq) * 2), Bv[ks], accS, 0, 0, 0);
;             S = accS;
;             { u32x2 w; w.x = cvt_pk_bf16(S[0], S[1]); w.y = cvt_pk_bf16(S[2], S[3]); *(u32x2*)(SlT + fr * 272 + (16 * wave + 4 * fq) * 2) = w; }
;             if (isQ) {
; #pragma unroll
;                 for (int ks = 0; ks < 2; ++ks) out = __builtin_amdgcn_mfma_f32_16x16x32_bf16(*(const bf16x8*)(QKl + (16 * i + fr) * 144 + (32 * ks + 8 * fq) * 2), Bv[ks], out, 0, 0, 0);
; #pragma unroll
;                 for (int j = 0; j < 4; ++j) ORAW[(size_t)(tg0 + 16 * i + 4 * fq + j) * 1024 + h * 128 + 16 * slice + fr] = bf16_1(out[j]);
;             }
;         }
.LBB0_193:
	s_add_i32 s54, s52, 0x1f8
	s_lshl_b32 s20, s54, 13
	s_lshl_b32 s52, s54, 14
	s_mov_b32 s21, s89
	s_add_u32 s52, s7, s52
	s_waitcnt vmcnt(7)
	ds_write_b128 v112, v[10:13] offset:34816
	s_waitcnt vmcnt(6)
	ds_write_b128 v104, v[14:17] offset:34816
	s_waitcnt vmcnt(5)
	ds_write_b128 v105, v[18:21] offset:53248
	s_addc_u32 s53, s29, 0
	v_lshl_add_u64 v[18:19], v[56:57], 0, s[20:21]
	s_lshl_b32 s20, s54, 2
	v_lshl_add_u64 v[10:11], v[50:51], 1, s[52:53]
	v_lshl_add_u64 v[14:15], v[62:63], 1, s[52:53]
	v_mov_b32_e32 v42, s20
	global_load_dwordx4 v[10:13], v[10:11], off
	s_waitcnt vmcnt(5)
	v_pk_mul_f32 v[40:41], v[40:41], v[0:1] op_sel_hi:[1,0]
	global_load_dwordx4 v[14:17], v[14:15], off
	v_pk_mul_f32 v[38:39], v[38:39], v[0:1] op_sel_hi:[1,0]
	global_load_dwordx4 v[18:21], v[18:19], off
	s_and_b64 vcc, exec, s[48:49]
	global_load_dword v72, v42, s[14:15]
	s_waitcnt lgkmcnt(0)
	s_barrier
	ds_read_b128 v[46:49], v115
	ds_read_b128 v[42:45], v115 offset:64
	ds_read_b128 v[76:79], v109 offset:34816
	s_waitcnt lgkmcnt(0)
	v_mfma_f32_16x16x32_bf16 v[38:41], v[76:79], v[46:49], v[38:41]
	ds_read_b128 v[76:79], v109 offset:34880
	s_waitcnt lgkmcnt(0)
	v_mfma_f32_16x16x32_bf16 v[38:41], v[76:79], v[42:45], v[38:41]
	s_nop 7
	v_cvt_pk_bf16_f32 v76, v38, v39
	v_cvt_pk_bf16_f32 v77, v40, v41
	ds_write_b64 v110, v[76:77] offset:64512
	s_cbranch_vccnz .LBB0_195
	ds_read_b128 v[76:79], v111 offset:53248
	s_lshl_b32 s20, s88, 1
	v_lshl_or_b32 v0, v113, 11, s20
	s_waitcnt lgkmcnt(0)
	v_mfma_f32_16x16x32_bf16 v[2:5], v[76:79], v[46:49], v[2:5]
	ds_read_b128 v[46:49], v111 offset:53312
	s_waitcnt lgkmcnt(0)
	v_mfma_f32_16x16x32_bf16 v[2:5], v[46:49], v[42:45], v[2:5]
	v_lshl_add_u64 v[42:43], v[70:71], 0, v[0:1]
	v_add_co_u32_e32 v44, vcc, 0x7c0000, v42
	s_nop 5
	v_cvt_pk_bf16_f32 v0, v3, s0
	v_addc_co_u32_e32 v45, vcc, 0, v43, vcc
	v_add_co_u32_e32 v42, vcc, 0x7c1000, v42
	global_store_short v[44:45], v0, off offset:2048
	v_cvt_pk_bf16_f32 v0, v4, s0
	v_addc_co_u32_e32 v43, vcc, 0, v43, vcc
	v_cvt_pk_bf16_f32 v46, v2, s0
	global_store_short v[42:43], v0, off
	v_cvt_pk_bf16_f32 v0, v5, s0
	global_store_short v[44:45], v46, off
	global_store_short v[42:43], v0, off offset:2048

; #define PREP_LOAD(p) do { _Pragma("unroll") for (int j = 0; j < 4; ++j) { const int rowi = (s - 3 + j >= 0) ? tg - 3 + j : tg; const bf16_t* row = QKV + (size_t)rowi * 3072 + (p) * 1024 + h * 128 + 16 * sub; \
;                 xr[(p) & 1][j][0] = *(const u32x4*)row; xr[(p) & 1][j][1] = *(const u32x4*)(row + 8); } } while (0)
; __device__ __forceinline__ void gdn_prep(KA a, int layer, unsigned char* lds, const int tid_, const int bid_) {
;     ...
;     for (int item = bid_; item < 2048; item += gridDim.x) {
;         const int c = item >> 3, h = item & 7, tg0 = c * 64;
;         const int tg = tg0 + tl, s = tg & (SEQ_ - 1);
;         if (h != h_loaded) {
;             if (tid < 384) { const int pj = tid >> 5, q4 = tid & 31; *(f32x4*)(cwl + pj * 128 + q4 * 4) = *(const f32x4*)(cw + (pj & 3) * 3072 + (pj >> 2) * 1024 + h * 128 + q4 * 4); }
;             h_loaded = h;
;             __syncthreads();
;         }
;         u32x4 xr[2][4][2];
;     ...
;         PREP_LOAD(0); PREP_LOAD(1);
;         if (wave == 0) {
;             float g = g_nx; const float bt = b_nx;
;             const int nit = item + gridDim.x;
;             if (nit < 2048) { g_nx = G[(size_t)((nit >> 3) * 64 + lane) * 8 + (nit & 7)]; b_nx = BETA[(size_t)((nit >> 3) * 64 + lane) * 8 + (nit & 7)]; }
; #pragma unroll
;             for (int o = 1; o < 64; o <<= 1) { const float t = __shfl_up(g, o); if (lane >= o) g += t; }
;             gcs[lane] = g; bts[lane] = bt;
;             if (lane == 63) ((float*)(ws + WS_EGL))[item] = expf(g);
.LBB0_213:
	s_lshl_b32 s19, s18, 3
	s_andn2_b32 s19, s19, 63
	v_add_u32_e32 v106, s19, v144
	v_and_b32_e32 v4, 0xfff, v106
	v_add_u32_e32 v5, -3, v106
	s_lshl_b32 s88, s31, 8
	v_cmp_gt_u32_e64 s[90:91], 3, v4
	v_lshl_add_u64 v[2:3], v[96:97], 0, s[88:89]
	v_mov_b64_e32 v[8:9], s[8:9]
	v_cndmask_b32_e64 v5, v5, v106, s[90:91]
	v_mad_i64_i32 v[6:7], s[20:21], v5, s26, v[2:3]
	global_load_dwordx4 v[54:57], v[6:7], off offset:16
	global_load_dwordx4 v[70:73], v[6:7], off
	v_add_u32_e32 v6, -2, v106
	v_cmp_gt_u32_e64 s[90:91], 2, v4
	v_mad_i64_i32 v[108:109], s[20:21], v106, s26, v[8:9]
	s_nop 0
	v_cndmask_b32_e64 v10, v6, v106, s[90:91]
	v_cmp_ne_u32_e64 s[90:91], 0, v4
	v_mad_i64_i32 v[6:7], s[20:21], v10, s26, v[2:3]
	s_nop 0
	v_subbrev_co_u32_e64 v12, s[90:91], 0, v106, s[90:91]
	global_load_dwordx4 v[58:61], v[6:7], off offset:16
	global_load_dwordx4 v[74:77], v[6:7], off
	v_mad_i64_i32 v[6:7], s[20:21], v12, s26, v[2:3]
	v_mad_i64_i32 v[2:3], s[20:21], v106, s26, v[2:3]
	global_load_dwordx4 v[62:65], v[6:7], off offset:16
	global_load_dwordx4 v[78:81], v[6:7], off
	global_load_dwordx4 v[50:53], v[2:3], off offset:16
	global_load_dwordx4 v[66:69], v[2:3], off
	v_mad_i64_i32 v[2:3], s[20:21], v5, s26, v[8:9]
	v_lshl_add_u64 v[6:7], v[2:3], 0, s[88:89]
	v_lshl_add_u64 v[6:7], v[6:7], 0, v[0:1]
	global_load_dwordx4 v[18:21], v[6:7], off offset:2064
	global_load_dwordx4 v[34:37], v[6:7], off offset:2048
	v_mad_i64_i32 v[6:7], s[20:21], v10, s26, v[8:9]
	v_lshl_add_u64 v[10:11], v[6:7], 0, s[88:89]
	v_lshl_add_u64 v[10:11], v[10:11], 0, v[0:1]
	v_mad_i64_i32 v[116:117], s[20:21], v12, s26, v[8:9]
	global_load_dwordx4 v[22:25], v[10:11], off offset:2064
	global_load_dwordx4 v[38:41], v[10:11], off offset:2048
	v_lshl_add_u64 v[10:11], v[116:117], 0, s[88:89]
	v_lshl_add_u64 v[8:9], v[108:109], 0, s[88:89]
	v_lshl_add_u64 v[10:11], v[10:11], 0, v[0:1]
	v_lshl_add_u64 v[8:9], v[8:9], 0, v[0:1]
	global_load_dwordx4 v[26:29], v[10:11], off offset:2064
	global_load_dwordx4 v[42:45], v[10:11], off offset:2048
	global_load_dwordx4 v[30:33], v[8:9], off offset:2064
	global_load_dwordx4 v[46:49], v[8:9], off offset:2048
	s_mov_b64 s[34:35], s[92:93]
	s_and_saveexec_b64 s[92:93], s[40:41]
	s_cbranch_execz .LBB0_219
	s_load_dword s19, s[94:95], 0x10
	s_load_dword s88, s[94:95], 0x0
	s_waitcnt vmcnt(24)
	v_mov_b32_e32 v8, v147
	v_mov_b32_e32 v5, v157
	s_waitcnt lgkmcnt(0)
	s_lshr_b32 s19, s19, 16
	s_cmp_lg_u32 s19, 0
	s_cselect_b64 s[20:21], -1, 0
	s_cmp_lg_u64 s[20:21], 0
	s_addc_u32 s19, s88, s18
	s_cmpk_gt_i32 s19, 0x7ff
	s_cbranch_scc1 .LBB0_216
	s_lshl_b32 s20, s19, 3
	s_andn2_b32 s20, s20, 63
	v_or_b32_e32 v8, s20, v198
	v_ashrrev_i32_e32 v9, 31, v8
	s_and_b32 s19, s19, 7
	v_lshlrev_b64 v[8:9], 5, v[8:9]
	v_lshl_or_b32 v8, s19, 2, v8
	v_lshl_add_u64 v[10:11], s[4:5], 0, v[8:9]
	v_lshl_add_u64 v[8:9], s[42:43], 0, v[8:9]
	global_load_dword v5, v[10:11], off
	s_nop 0
	global_load_dword v8, v[8:9], off

; __device__ __forceinline__ unsigned short bf16_1(float x) { return (unsigned short)(cvt_pk_bf16(x, 0.f) & 0xffffu); }
; __device__ __forceinline__ void phase_a(KA a, int layer, const float* xin, unsigned char* lds, const int tid_, const int bid_) {
;     ...
;     __syncthreads();
;     bf16_t* WlT = (bf16_t*)lds;
;     for (int idx = tid; idx < D_ * 16; idx += 512) { const int k = idx >> 4, j = idx & 15; WlT[j * 2056 + k] = bf16_1(w_in[(size_t)k * INC + 4096 + j]); }
;     __syncthreads();
.LBB0_391:
	s_or_b64 exec, exec, s[10:11]
	s_mov_b32 s10, 0x8000
	v_cmp_gt_i32_e32 vcc, s10, v198
	v_and_b32_e32 v38, 15, v198
	s_movk_i32 s10, 0x1010
	s_mov_b32 s21, 0x3fb8aa3b
	s_mov_b32 s18, 0xc2ce8ed0
	s_mov_b32 s19, 0x42b17218
	v_mov_b32_e32 v2, v198
	v_mad_u32_u24 v39, v38, s10, 0
	s_waitcnt vmcnt(0)
	s_barrier
	s_and_saveexec_b64 s[10:11], vcc
	s_cbranch_execz .LBB0_403
	v_lshrrev_b32_e32 v2, 4, v198
	v_lshlrev_b32_e32 v0, 2, v38
	v_mul_u32_u24_e32 v3, 0xa040, v2
	s_movk_i32 s14, 0x4000
	s_mov_b64 s[12:13], s[8:9]
	v_add3_u32 v3, v3, v0, s14
	v_lshl_add_u32 v4, v2, 1, v39
	global_load_dword v120, v3, s[12:13]
	s_add_u32 s12, s12, 0x140800
	s_addc_u32 s13, s13, 0
	global_load_dword v121, v3, s[12:13]
	s_add_u32 s12, s12, 0x140800
	s_addc_u32 s13, s13, 0
	global_load_dword v122, v3, s[12:13]
	s_add_u32 s12, s12, 0x140800
	s_addc_u32 s13, s13, 0
	global_load_dword v123, v3, s[12:13]
	s_add_u32 s12, s12, 0x140800
	s_addc_u32 s13, s13, 0
	global_load_dword v124, v3, s[12:13]
	s_add_u32 s12, s12, 0x140800
	s_addc_u32 s13, s13, 0
	global_load_dword v125, v3, s[12:13]
	s_add_u32 s12, s12, 0x140800
	s_addc_u32 s13, s13, 0
	global_load_dword v126, v3, s[12:13]
	s_add_u32 s12, s12, 0x140800
	s_addc_u32 s13, s13, 0
	global_load_dword v127, v3, s[12:13]
	s_add_u32 s12, s12, 0x140800
	s_addc_u32 s13, s13, 0
	global_load_dword v128, v3, s[12:13]
	s_add_u32 s12, s12, 0x140800
	s_addc_u32 s13, s13, 0
	global_load_dword v129, v3, s[12:13]
	s_add_u32 s12, s12, 0x140800
	s_addc_u32 s13, s13, 0
	global_load_dword v130, v3, s[12:13]
	s_add_u32 s12, s12, 0x140800
	s_addc_u32 s13, s13, 0
	global_load_dword v131, v3, s[12:13]
	s_add_u32 s12, s12, 0x140800
	s_addc_u32 s13, s13, 0
	global_load_dword v132, v3, s[12:13]
	s_add_u32 s12, s12, 0x140800
	s_addc_u32 s13, s13, 0
	global_load_dword v133, v3, s[12:13]
	s_add_u32 s12, s12, 0x140800
	s_addc_u32 s13, s13, 0
	global_load_dword v134, v3, s[12:13]
	s_add_u32 s12, s12, 0x140800
	s_addc_u32 s13, s13, 0
	global_load_dword v135, v3, s[12:13]
	s_add_u32 s12, s12, 0x140800
	s_addc_u32 s13, s13, 0
	global_load_dword v136, v3, s[12:13]
	s_add_u32 s12, s12, 0x140800
	s_addc_u32 s13, s13, 0
	global_load_dword v137, v3, s[12:13]
	s_add_u32 s12, s12, 0x140800
	s_addc_u32 s13, s13, 0
	global_load_dword v138, v3, s[12:13]
	s_add_u32 s12, s12, 0x140800
	s_addc_u32 s13, s13, 0
	global_load_dword v139, v3, s[12:13]
	s_add_u32 s12, s12, 0x140800
	s_addc_u32 s13, s13, 0
	global_load_dword v140, v3, s[12:13]
	s_add_u32 s12, s12, 0x140800
	s_addc_u32 s13, s13, 0
	global_load_dword v141, v3, s[12:13]
	s_add_u32 s12, s12, 0x140800
	s_addc_u32 s13, s13, 0
	global_load_dword v142, v3, s[12:13]
	s_add_u32 s12, s12, 0x140800
	s_addc_u32 s13, s13, 0
	global_load_dword v143, v3, s[12:13]
	s_add_u32 s12, s12, 0x140800
	s_addc_u32 s13, s13, 0
	global_load_dword v144, v3, s[12:13]
	s_add_u32 s12, s12, 0x140800
	s_addc_u32 s13, s13, 0
	global_load_dword v145, v3, s[12:13]
	s_add_u32 s12, s12, 0x140800
	s_addc_u32 s13, s13, 0
	global_load_dword v146, v3, s[12:13]
	s_add_u32 s12, s12, 0x140800
	s_addc_u32 s13, s13, 0
	global_load_dword v147, v3, s[12:13]
	s_add_u32 s12, s12, 0x140800
	s_addc_u32 s13, s13, 0
	global_load_dword v148, v3, s[12:13]
	s_add_u32 s12, s12, 0x140800
	s_addc_u32 s13, s13, 0
	global_load_dword v149, v3, s[12:13]
	s_add_u32 s12, s12, 0x140800
	s_addc_u32 s13, s13, 0
	global_load_dword v150, v3, s[12:13]
	s_add_u32 s12, s12, 0x140800
	s_addc_u32 s13, s13, 0
	global_load_dword v151, v3, s[12:13]
	s_add_u32 s12, s12, 0x140800
	s_addc_u32 s13, s13, 0
	global_load_dword v152, v3, s[12:13]
	s_add_u32 s12, s12, 0x140800
	s_addc_u32 s13, s13, 0
	global_load_dword v153, v3, s[12:13]
	s_add_u32 s12, s12, 0x140800
	s_addc_u32 s13, s13, 0
	global_load_dword v154, v3, s[12:13]
	s_add_u32 s12, s12, 0x140800
	s_addc_u32 s13, s13, 0
	global_load_dword v155, v3, s[12:13]
	s_add_u32 s12, s12, 0x140800
	s_addc_u32 s13, s13, 0
	global_load_dword v156, v3, s[12:13]
	s_add_u32 s12, s12, 0x140800
	s_addc_u32 s13, s13, 0
	global_load_dword v157, v3, s[12:13]
	s_add_u32 s12, s12, 0x140800
	s_addc_u32 s13, s13, 0
	global_load_dword v158, v3, s[12:13]
	s_add_u32 s12, s12, 0x140800
	s_addc_u32 s13, s13, 0
	global_load_dword v159, v3, s[12:13]
	s_add_u32 s12, s12, 0x140800
	s_addc_u32 s13, s13, 0
	global_load_dword v160, v3, s[12:13]
	s_add_u32 s12, s12, 0x140800
	s_addc_u32 s13, s13, 0
	global_load_dword v161, v3, s[12:13]
	s_add_u32 s12, s12, 0x140800
	s_addc_u32 s13, s13, 0
	global_load_dword v162, v3, s[12:13]
	s_add_u32 s12, s12, 0x140800
	s_addc_u32 s13, s13, 0
	global_load_dword v163, v3, s[12:13]
	s_add_u32 s12, s12, 0x140800
	s_addc_u32 s13, s13, 0
	global_load_dword v164, v3, s[12:13]
	s_add_u32 s12, s12, 0x140800
	s_addc_u32 s13, s13, 0
	global_load_dword v165, v3, s[12:13]
	s_add_u32 s12, s12, 0x140800
	s_addc_u32 s13, s13, 0
	global_load_dword v166, v3, s[12:13]
	s_add_u32 s12, s12, 0x140800
	s_addc_u32 s13, s13, 0
	global_load_dword v167, v3, s[12:13]
	s_add_u32 s12, s12, 0x140800
	s_addc_u32 s13, s13, 0
	global_load_dword v168, v3, s[12:13]
	s_add_u32 s12, s12, 0x140800
	s_addc_u32 s13, s13, 0
	global_load_dword v169, v3, s[12:13]
	s_add_u32 s12, s12, 0x140800
	s_addc_u32 s13, s13, 0
	global_load_dword v170, v3, s[12:13]
	s_add_u32 s12, s12, 0x140800
	s_addc_u32 s13, s13, 0
	global_load_dword v171, v3, s[12:13]
	s_add_u32 s12, s12, 0x140800
	s_addc_u32 s13, s13, 0
	global_load_dword v172, v3, s[12:13]
	s_add_u32 s12, s12, 0x140800
	s_addc_u32 s13, s13, 0
	global_load_dword v173, v3, s[12:13]
	s_add_u32 s12, s12, 0x140800
	s_addc_u32 s13, s13, 0
	global_load_dword v174, v3, s[12:13]
	s_add_u32 s12, s12, 0x140800
	s_addc_u32 s13, s13, 0
	global_load_dword v175, v3, s[12:13]
	s_add_u32 s12, s12, 0x140800
	s_addc_u32 s13, s13, 0
	global_load_dword v176, v3, s[12:13]
	s_add_u32 s12, s12, 0x140800
	s_addc_u32 s13, s13, 0
	global_load_dword v177, v3, s[12:13]
	s_add_u32 s12, s12, 0x140800
	s_addc_u32 s13, s13, 0
	global_load_dword v178, v3, s[12:13]
	s_add_u32 s12, s12, 0x140800
	s_addc_u32 s13, s13, 0
	global_load_dword v179, v3, s[12:13]
	s_add_u32 s12, s12, 0x140800
	s_addc_u32 s13, s13, 0
	global_load_dword v180, v3, s[12:13]
	s_add_u32 s12, s12, 0x140800
	s_addc_u32 s13, s13, 0
	global_load_dword v181, v3, s[12:13]
	s_add_u32 s12, s12, 0x140800
	s_addc_u32 s13, s13, 0
	global_load_dword v182, v3, s[12:13]
	s_add_u32 s12, s12, 0x140800
	s_addc_u32 s13, s13, 0
	global_load_dword v183, v3, s[12:13]
	s_waitcnt vmcnt(62)
; __device__ __forceinline__ unsigned short bf16_1(float x) { return (unsigned short)(cvt_pk_bf16(x, 0.f) & 0xffffu); }
; __device__ __forceinline__ void phase_a(KA a, int layer, const float* xin, unsigned char* lds, const int tid_, const int bid_) {
;     ...
;     for (int idx = tid; idx < D_ * 16; idx += 512) { const int k = idx >> 4, j = idx & 15; WlT[j * 2056 + k] = bf16_1(w_in[(size_t)k * INC + 4096 + j]); }
	v_cvt_pk_bf16_f32 v5, v120, v121
	s_nop 0
	ds_write_b16 v4, v5 offset:0
	ds_write_b16_d16_hi v4, v5 offset:64
	s_waitcnt vmcnt(60)
	v_cvt_pk_bf16_f32 v6, v122, v123
	s_nop 0
	ds_write_b16 v4, v6 offset:128
	ds_write_b16_d16_hi v4, v6 offset:192
	s_waitcnt vmcnt(58)
	v_cvt_pk_bf16_f32 v7, v124, v125
	s_nop 0
	ds_write_b16 v4, v7 offset:256
	ds_write_b16_d16_hi v4, v7 offset:320
	s_waitcnt vmcnt(56)
	v_cvt_pk_bf16_f32 v8, v126, v127
	s_nop 0
	ds_write_b16 v4, v8 offset:384
	ds_write_b16_d16_hi v4, v8 offset:448
	s_waitcnt vmcnt(54)
	v_cvt_pk_bf16_f32 v5, v128, v129
	s_nop 0
	ds_write_b16 v4, v5 offset:512
	ds_write_b16_d16_hi v4, v5 offset:576
	s_waitcnt vmcnt(52)
	v_cvt_pk_bf16_f32 v6, v130, v131
	s_nop 0
	ds_write_b16 v4, v6 offset:640
	ds_write_b16_d16_hi v4, v6 offset:704
	s_waitcnt vmcnt(50)
	v_cvt_pk_bf16_f32 v7, v132, v133
	s_nop 0
	ds_write_b16 v4, v7 offset:768
	ds_write_b16_d16_hi v4, v7 offset:832
	s_waitcnt vmcnt(48)
	v_cvt_pk_bf16_f32 v8, v134, v135
	s_nop 0
	ds_write_b16 v4, v8 offset:896
	ds_write_b16_d16_hi v4, v8 offset:960
	s_waitcnt vmcnt(46)
	v_cvt_pk_bf16_f32 v5, v136, v137
	s_nop 0
	ds_write_b16 v4, v5 offset:1024
	ds_write_b16_d16_hi v4, v5 offset:1088
	s_waitcnt vmcnt(44)
	v_cvt_pk_bf16_f32 v6, v138, v139
	s_nop 0
	ds_write_b16 v4, v6 offset:1152
	ds_write_b16_d16_hi v4, v6 offset:1216
	s_waitcnt vmcnt(42)
	v_cvt_pk_bf16_f32 v7, v140, v141
	s_nop 0
	ds_write_b16 v4, v7 offset:1280
	ds_write_b16_d16_hi v4, v7 offset:1344
	s_waitcnt vmcnt(40)
	v_cvt_pk_bf16_f32 v8, v142, v143
	s_nop 0
	ds_write_b16 v4, v8 offset:1408
	ds_write_b16_d16_hi v4, v8 offset:1472
	s_waitcnt vmcnt(38)
	v_cvt_pk_bf16_f32 v5, v144, v145
	s_nop 0
	ds_write_b16 v4, v5 offset:1536
	ds_write_b16_d16_hi v4, v5 offset:1600
	s_waitcnt vmcnt(36)
	v_cvt_pk_bf16_f32 v6, v146, v147
	s_nop 0
	ds_write_b16 v4, v6 offset:1664
	ds_write_b16_d16_hi v4, v6 offset:1728
	s_waitcnt vmcnt(34)
	v_cvt_pk_bf16_f32 v7, v148, v149
	s_nop 0
	ds_write_b16 v4, v7 offset:1792
	ds_write_b16_d16_hi v4, v7 offset:1856
	s_waitcnt vmcnt(32)
	v_cvt_pk_bf16_f32 v8, v150, v151
	s_nop 0
	ds_write_b16 v4, v8 offset:1920
	ds_write_b16_d16_hi v4, v8 offset:1984
	s_waitcnt vmcnt(30)
	v_cvt_pk_bf16_f32 v5, v152, v153
	s_nop 0
	ds_write_b16 v4, v5 offset:2048
	ds_write_b16_d16_hi v4, v5 offset:2112
	s_waitcnt vmcnt(28)
	v_cvt_pk_bf16_f32 v6, v154, v155
	s_nop 0
	ds_write_b16 v4, v6 offset:2176
	ds_write_b16_d16_hi v4, v6 offset:2240
	s_waitcnt vmcnt(26)
	v_cvt_pk_bf16_f32 v7, v156, v157
	s_nop 0
	ds_write_b16 v4, v7 offset:2304
	ds_write_b16_d16_hi v4, v7 offset:2368
	s_waitcnt vmcnt(24)
	v_cvt_pk_bf16_f32 v8, v158, v159
	s_nop 0
	ds_write_b16 v4, v8 offset:2432
	ds_write_b16_d16_hi v4, v8 offset:2496
	s_waitcnt vmcnt(22)
	v_cvt_pk_bf16_f32 v5, v160, v161
	s_nop 0
	ds_write_b16 v4, v5 offset:2560
	ds_write_b16_d16_hi v4, v5 offset:2624
	s_waitcnt vmcnt(20)
	v_cvt_pk_bf16_f32 v6, v162, v163
	s_nop 0
	ds_write_b16 v4, v6 offset:2688
	ds_write_b16_d16_hi v4, v6 offset:2752
	s_waitcnt vmcnt(18)
	v_cvt_pk_bf16_f32 v7, v164, v165
	s_nop 0
	ds_write_b16 v4, v7 offset:2816
	ds_write_b16_d16_hi v4, v7 offset:2880
	s_waitcnt vmcnt(16)
	v_cvt_pk_bf16_f32 v8, v166, v167
	s_nop 0
	ds_write_b16 v4, v8 offset:2944
	ds_write_b16_d16_hi v4, v8 offset:3008
	s_waitcnt vmcnt(14)
	v_cvt_pk_bf16_f32 v5, v168, v169
	s_nop 0
	ds_write_b16 v4, v5 offset:3072
	ds_write_b16_d16_hi v4, v5 offset:3136
	s_waitcnt vmcnt(12)
	v_cvt_pk_bf16_f32 v6, v170, v171
	s_nop 0
	ds_write_b16 v4, v6 offset:3200
	ds_write_b16_d16_hi v4, v6 offset:3264
	s_waitcnt vmcnt(10)
	v_cvt_pk_bf16_f32 v7, v172, v173
	s_nop 0
	ds_write_b16 v4, v7 offset:3328
	ds_write_b16_d16_hi v4, v7 offset:3392
	s_waitcnt vmcnt(8)
	v_cvt_pk_bf16_f32 v8, v174, v175
	s_nop 0
	ds_write_b16 v4, v8 offset:3456
	ds_write_b16_d16_hi v4, v8 offset:3520
	s_waitcnt vmcnt(6)
	v_cvt_pk_bf16_f32 v5, v176, v177
	s_nop 0
	ds_write_b16 v4, v5 offset:3584
	ds_write_b16_d16_hi v4, v5 offset:3648
	s_waitcnt vmcnt(4)
	v_cvt_pk_bf16_f32 v6, v178, v179
	s_nop 0
	ds_write_b16 v4, v6 offset:3712
	ds_write_b16_d16_hi v4, v6 offset:3776
	s_waitcnt vmcnt(2)
	v_cvt_pk_bf16_f32 v7, v180, v181
	s_nop 0
	ds_write_b16 v4, v7 offset:3840
	ds_write_b16_d16_hi v4, v7 offset:3904
	s_waitcnt vmcnt(0)
	v_cvt_pk_bf16_f32 v8, v182, v183
	s_nop 0
	ds_write_b16 v4, v8 offset:3968
	ds_write_b16_d16_hi v4, v8 offset:4032
